# lru_carry: all 128 chain loads issued up front (one memory round trip instead of 64 serial); tconv all six with pair prefetch
# speedup vs baseline: 1.0070x; 1.0070x over previous
; __device__ void lru_carry(const Params& p) {
;     const float* LA = (const float*)(p.ws + OFF_LRUA); const float* LH = (const float*)(p.ws + OFF_LRUH); float* LC = (float*)(p.ws + OFF_LRUC);
;     for (int idx = blockIdx.x * 512 + threadIdx.x; idx < 4 * 2048; idx += gridDim.x * 512) { const int b = idx >> 11, cg_ = idx & 2047; float c = 0.f;
; #pragma unroll 8
;         for (int k = 0; k < 64; ++k) { const size_t o = (size_t)(b * 64 + k) * 2048 + cg_; LC[o] = c; c = LA[o] * c + LH[o]; } }
; }
.LBB0_374:
	v_ashrrev_i32_e32 v2, 5, v1
	v_and_b32_e32 v2, 0xffffffc0, v2
	v_ashrrev_i32_e32 v3, 31, v2
	v_and_b32_e32 v6, 0x7ff, v5
	v_lshlrev_b64 v[2:3], 13, v[2:3]
	v_lshl_or_b32 v2, v6, 2, v2
	v_mov_b32_e32 v7, v2
	v_lshl_add_u64 v[2:3], s[64:65], 0, v[2:3]
	v_mov_b32_e32 v6, 0
	s_mov_b64 s[20:21], 0
	s_add_u32 s36, s64, 0x1f100000
	s_addc_u32 s37, s65, 0
	s_add_u32 s38, s64, 0x1f300000
	s_addc_u32 s39, s65, 0
	s_add_u32 s40, s64, 0x1f500000
	s_addc_u32 s41, s65, 0
	v_mov_b32_e32 v10, v7
	global_load_dword v180, v7, s[36:37]
	global_load_dword v70, v7, s[38:39]
	v_add_u32_e32 v7, 0x2000, v7
	global_load_dword v181, v7, s[36:37]
	global_load_dword v71, v7, s[38:39]
	v_add_u32_e32 v7, 0x2000, v7
	global_load_dword v182, v7, s[36:37]
	global_load_dword v72, v7, s[38:39]
	v_add_u32_e32 v7, 0x2000, v7
	global_load_dword v183, v7, s[36:37]
	global_load_dword v73, v7, s[38:39]
	v_add_u32_e32 v7, 0x2000, v7
	global_load_dword v184, v7, s[36:37]
	global_load_dword v74, v7, s[38:39]
	v_add_u32_e32 v7, 0x2000, v7
	global_load_dword v185, v7, s[36:37]
	global_load_dword v75, v7, s[38:39]
	v_add_u32_e32 v7, 0x2000, v7
	global_load_dword v186, v7, s[36:37]
	global_load_dword v76, v7, s[38:39]
	v_add_u32_e32 v7, 0x2000, v7
	global_load_dword v187, v7, s[36:37]
	global_load_dword v77, v7, s[38:39]
	v_add_u32_e32 v7, 0x2000, v7
	global_load_dword v188, v7, s[36:37]
	global_load_dword v78, v7, s[38:39]
	v_add_u32_e32 v7, 0x2000, v7
	global_load_dword v189, v7, s[36:37]
	global_load_dword v79, v7, s[38:39]
	v_add_u32_e32 v7, 0x2000, v7
	global_load_dword v190, v7, s[36:37]
	global_load_dword v80, v7, s[38:39]
	v_add_u32_e32 v7, 0x2000, v7
	global_load_dword v191, v7, s[36:37]
	global_load_dword v81, v7, s[38:39]
	v_add_u32_e32 v7, 0x2000, v7
	global_load_dword v192, v7, s[36:37]
	global_load_dword v82, v7, s[38:39]
	v_add_u32_e32 v7, 0x2000, v7
	global_load_dword v193, v7, s[36:37]
	global_load_dword v83, v7, s[38:39]
	v_add_u32_e32 v7, 0x2000, v7
	global_load_dword v194, v7, s[36:37]
	global_load_dword v84, v7, s[38:39]
	v_add_u32_e32 v7, 0x2000, v7
	global_load_dword v195, v7, s[36:37]
	global_load_dword v85, v7, s[38:39]
	v_add_u32_e32 v7, 0x2000, v7
	global_load_dword v196, v7, s[36:37]
	global_load_dword v86, v7, s[38:39]
	v_add_u32_e32 v7, 0x2000, v7
	global_load_dword v197, v7, s[36:37]
	global_load_dword v87, v7, s[38:39]
	v_add_u32_e32 v7, 0x2000, v7
	global_load_dword v198, v7, s[36:37]
	global_load_dword v88, v7, s[38:39]
	v_add_u32_e32 v7, 0x2000, v7
	global_load_dword v199, v7, s[36:37]
	global_load_dword v89, v7, s[38:39]
	v_add_u32_e32 v7, 0x2000, v7
	global_load_dword v200, v7, s[36:37]
	global_load_dword v98, v7, s[38:39]
	v_add_u32_e32 v7, 0x2000, v7
	global_load_dword v201, v7, s[36:37]
	global_load_dword v99, v7, s[38:39]
	v_add_u32_e32 v7, 0x2000, v7
	global_load_dword v202, v7, s[36:37]
	global_load_dword v100, v7, s[38:39]
	v_add_u32_e32 v7, 0x2000, v7
	global_load_dword v203, v7, s[36:37]
	global_load_dword v101, v7, s[38:39]
	v_add_u32_e32 v7, 0x2000, v7
	global_load_dword v204, v7, s[36:37]
	global_load_dword v102, v7, s[38:39]
	v_add_u32_e32 v7, 0x2000, v7
	global_load_dword v205, v7, s[36:37]
	global_load_dword v103, v7, s[38:39]
	v_add_u32_e32 v7, 0x2000, v7
	global_load_dword v206, v7, s[36:37]
	global_load_dword v104, v7, s[38:39]
	v_add_u32_e32 v7, 0x2000, v7
	global_load_dword v207, v7, s[36:37]
	global_load_dword v105, v7, s[38:39]
	v_add_u32_e32 v7, 0x2000, v7
	global_load_dword v208, v7, s[36:37]
	global_load_dword v106, v7, s[38:39]
	v_add_u32_e32 v7, 0x2000, v7
	global_load_dword v209, v7, s[36:37]
	global_load_dword v107, v7, s[38:39]
	v_add_u32_e32 v7, 0x2000, v7
	global_load_dword v210, v7, s[36:37]
	global_load_dword v108, v7, s[38:39]
	v_add_u32_e32 v7, 0x2000, v7
	global_load_dword v211, v7, s[36:37]
	global_load_dword v109, v7, s[38:39]
	v_add_u32_e32 v7, 0x2000, v7
	global_load_dword v212, v7, s[36:37]
	global_load_dword v110, v7, s[38:39]
	v_add_u32_e32 v7, 0x2000, v7
	global_load_dword v213, v7, s[36:37]
	global_load_dword v111, v7, s[38:39]
	v_add_u32_e32 v7, 0x2000, v7
	global_load_dword v214, v7, s[36:37]
	global_load_dword v112, v7, s[38:39]
	v_add_u32_e32 v7, 0x2000, v7
	global_load_dword v215, v7, s[36:37]
	global_load_dword v113, v7, s[38:39]
	v_add_u32_e32 v7, 0x2000, v7
	global_load_dword v216, v7, s[36:37]
	global_load_dword v114, v7, s[38:39]
	v_add_u32_e32 v7, 0x2000, v7
	global_load_dword v217, v7, s[36:37]
	global_load_dword v115, v7, s[38:39]
	v_add_u32_e32 v7, 0x2000, v7
	global_load_dword v218, v7, s[36:37]
	global_load_dword v116, v7, s[38:39]
	v_add_u32_e32 v7, 0x2000, v7
	global_load_dword v219, v7, s[36:37]
	global_load_dword v117, v7, s[38:39]
	v_add_u32_e32 v7, 0x2000, v7
	global_load_dword v220, v7, s[36:37]
	global_load_dword v118, v7, s[38:39]
	v_add_u32_e32 v7, 0x2000, v7
	global_load_dword v221, v7, s[36:37]
	global_load_dword v119, v7, s[38:39]
	v_add_u32_e32 v7, 0x2000, v7
	global_load_dword v222, v7, s[36:37]
	global_load_dword v120, v7, s[38:39]
	v_add_u32_e32 v7, 0x2000, v7
	global_load_dword v223, v7, s[36:37]
	global_load_dword v121, v7, s[38:39]
	v_add_u32_e32 v7, 0x2000, v7
	global_load_dword v224, v7, s[36:37]
	global_load_dword v122, v7, s[38:39]
	v_add_u32_e32 v7, 0x2000, v7
	global_load_dword v225, v7, s[36:37]
	global_load_dword v123, v7, s[38:39]
	v_add_u32_e32 v7, 0x2000, v7
	global_load_dword v226, v7, s[36:37]
	global_load_dword v142, v7, s[38:39]
	v_add_u32_e32 v7, 0x2000, v7
	global_load_dword v227, v7, s[36:37]
	global_load_dword v143, v7, s[38:39]
	v_add_u32_e32 v7, 0x2000, v7
	global_load_dword v228, v7, s[36:37]
	global_load_dword v144, v7, s[38:39]
; __device__ void lru_carry(const Params& p) {
;     ...
;     for (int idx = blockIdx.x * 512 + threadIdx.x; idx < 4 * 2048; idx += gridDim.x * 512) { const int b = idx >> 11, cg_ = idx & 2047; float c = 0.f;
; #pragma unroll 8
;         for (int k = 0; k < 64; ++k) { const size_t o = (size_t)(b * 64 + k) * 2048 + cg_; LC[o] = c; c = LA[o] * c + LH[o]; } }
	v_add_u32_e32 v7, 0x2000, v7
	global_load_dword v229, v7, s[36:37]
	global_load_dword v145, v7, s[38:39]
	v_add_u32_e32 v7, 0x2000, v7
	global_load_dword v230, v7, s[36:37]
	global_load_dword v146, v7, s[38:39]
	v_add_u32_e32 v7, 0x2000, v7
	global_load_dword v231, v7, s[36:37]
	global_load_dword v147, v7, s[38:39]
	v_add_u32_e32 v7, 0x2000, v7
	global_load_dword v232, v7, s[36:37]
	global_load_dword v148, v7, s[38:39]
	v_add_u32_e32 v7, 0x2000, v7
	global_load_dword v233, v7, s[36:37]
	global_load_dword v149, v7, s[38:39]
	v_add_u32_e32 v7, 0x2000, v7
	global_load_dword v234, v7, s[36:37]
	global_load_dword v150, v7, s[38:39]
	v_add_u32_e32 v7, 0x2000, v7
	global_load_dword v235, v7, s[36:37]
	global_load_dword v151, v7, s[38:39]
	v_add_u32_e32 v7, 0x2000, v7
	global_load_dword v236, v7, s[36:37]
	global_load_dword v152, v7, s[38:39]
	v_add_u32_e32 v7, 0x2000, v7
	global_load_dword v237, v7, s[36:37]
	global_load_dword v153, v7, s[38:39]
	v_add_u32_e32 v7, 0x2000, v7
	global_load_dword v238, v7, s[36:37]
	global_load_dword v154, v7, s[38:39]
	v_add_u32_e32 v7, 0x2000, v7
	global_load_dword v239, v7, s[36:37]
	global_load_dword v155, v7, s[38:39]
	v_add_u32_e32 v7, 0x2000, v7
	global_load_dword v240, v7, s[36:37]
	global_load_dword v156, v7, s[38:39]
	v_add_u32_e32 v7, 0x2000, v7
	global_load_dword v241, v7, s[36:37]
	global_load_dword v157, v7, s[38:39]
	v_add_u32_e32 v7, 0x2000, v7
	global_load_dword v242, v7, s[36:37]
	global_load_dword v158, v7, s[38:39]
	v_add_u32_e32 v7, 0x2000, v7
	global_load_dword v243, v7, s[36:37]
	global_load_dword v159, v7, s[38:39]
	v_add_u32_e32 v7, 0x2000, v7
	s_waitcnt vmcnt(0)
; __device__ void lru_carry(const Params& p) {
;     const float* LA = (const float*)(p.ws + OFF_LRUA); const float* LH = (const float*)(p.ws + OFF_LRUH); float* LC = (float*)(p.ws + OFF_LRUC);
;     for (int idx = blockIdx.x * 512 + threadIdx.x; idx < 4 * 2048; idx += gridDim.x * 512) { const int b = idx >> 11, cg_ = idx & 2047; float c = 0.f;
; #pragma unroll 8
;         for (int k = 0; k < 64; ++k) { const size_t o = (size_t)(b * 64 + k) * 2048 + cg_; LC[o] = c; c = LA[o] * c + LH[o]; } }
; }
	global_store_dword v10, v6, s[40:41]
	v_add_u32_e32 v10, 0x2000, v10
	v_fmac_f32_e32 v70, v6, v180
	global_store_dword v10, v70, s[40:41]
	v_add_u32_e32 v10, 0x2000, v10
	v_fmac_f32_e32 v71, v70, v181
	global_store_dword v10, v71, s[40:41]
	v_add_u32_e32 v10, 0x2000, v10
	v_fmac_f32_e32 v72, v71, v182
	global_store_dword v10, v72, s[40:41]
	v_add_u32_e32 v10, 0x2000, v10
	v_fmac_f32_e32 v73, v72, v183
	global_store_dword v10, v73, s[40:41]
	v_add_u32_e32 v10, 0x2000, v10
	v_fmac_f32_e32 v74, v73, v184
	global_store_dword v10, v74, s[40:41]
	v_add_u32_e32 v10, 0x2000, v10
	v_fmac_f32_e32 v75, v74, v185
	global_store_dword v10, v75, s[40:41]
	v_add_u32_e32 v10, 0x2000, v10
	v_fmac_f32_e32 v76, v75, v186
	global_store_dword v10, v76, s[40:41]
	v_add_u32_e32 v10, 0x2000, v10
	v_fmac_f32_e32 v77, v76, v187
	global_store_dword v10, v77, s[40:41]
	v_add_u32_e32 v10, 0x2000, v10
	v_fmac_f32_e32 v78, v77, v188
	global_store_dword v10, v78, s[40:41]
	v_add_u32_e32 v10, 0x2000, v10
	v_fmac_f32_e32 v79, v78, v189
	global_store_dword v10, v79, s[40:41]
	v_add_u32_e32 v10, 0x2000, v10
	v_fmac_f32_e32 v80, v79, v190
	global_store_dword v10, v80, s[40:41]
	v_add_u32_e32 v10, 0x2000, v10
	v_fmac_f32_e32 v81, v80, v191
	global_store_dword v10, v81, s[40:41]
	v_add_u32_e32 v10, 0x2000, v10
	v_fmac_f32_e32 v82, v81, v192
	global_store_dword v10, v82, s[40:41]
	v_add_u32_e32 v10, 0x2000, v10
	v_fmac_f32_e32 v83, v82, v193
	global_store_dword v10, v83, s[40:41]
	v_add_u32_e32 v10, 0x2000, v10
	v_fmac_f32_e32 v84, v83, v194
	global_store_dword v10, v84, s[40:41]
	v_add_u32_e32 v10, 0x2000, v10
	v_fmac_f32_e32 v85, v84, v195
	global_store_dword v10, v85, s[40:41]
	v_add_u32_e32 v10, 0x2000, v10
	v_fmac_f32_e32 v86, v85, v196
	global_store_dword v10, v86, s[40:41]
	v_add_u32_e32 v10, 0x2000, v10
	v_fmac_f32_e32 v87, v86, v197
	global_store_dword v10, v87, s[40:41]
	v_add_u32_e32 v10, 0x2000, v10
	v_fmac_f32_e32 v88, v87, v198
	global_store_dword v10, v88, s[40:41]
	v_add_u32_e32 v10, 0x2000, v10
	v_fmac_f32_e32 v89, v88, v199
	global_store_dword v10, v89, s[40:41]
	v_add_u32_e32 v10, 0x2000, v10
	v_fmac_f32_e32 v98, v89, v200
	global_store_dword v10, v98, s[40:41]
	v_add_u32_e32 v10, 0x2000, v10
	v_fmac_f32_e32 v99, v98, v201
	global_store_dword v10, v99, s[40:41]
	v_add_u32_e32 v10, 0x2000, v10
	v_fmac_f32_e32 v100, v99, v202
	global_store_dword v10, v100, s[40:41]
	v_add_u32_e32 v10, 0x2000, v10
	v_fmac_f32_e32 v101, v100, v203
	global_store_dword v10, v101, s[40:41]
	v_add_u32_e32 v10, 0x2000, v10
	v_fmac_f32_e32 v102, v101, v204
	global_store_dword v10, v102, s[40:41]
	v_add_u32_e32 v10, 0x2000, v10
	v_fmac_f32_e32 v103, v102, v205
	global_store_dword v10, v103, s[40:41]
	v_add_u32_e32 v10, 0x2000, v10
	v_fmac_f32_e32 v104, v103, v206
	global_store_dword v10, v104, s[40:41]
	v_add_u32_e32 v10, 0x2000, v10
	v_fmac_f32_e32 v105, v104, v207
	global_store_dword v10, v105, s[40:41]
	v_add_u32_e32 v10, 0x2000, v10
	v_fmac_f32_e32 v106, v105, v208
	global_store_dword v10, v106, s[40:41]
	v_add_u32_e32 v10, 0x2000, v10
	v_fmac_f32_e32 v107, v106, v209
	global_store_dword v10, v107, s[40:41]
	v_add_u32_e32 v10, 0x2000, v10
	v_fmac_f32_e32 v108, v107, v210
	global_store_dword v10, v108, s[40:41]
	v_add_u32_e32 v10, 0x2000, v10
	v_fmac_f32_e32 v109, v108, v211
	global_store_dword v10, v109, s[40:41]
	v_add_u32_e32 v10, 0x2000, v10
	v_fmac_f32_e32 v110, v109, v212
	global_store_dword v10, v110, s[40:41]
	v_add_u32_e32 v10, 0x2000, v10
	v_fmac_f32_e32 v111, v110, v213
	global_store_dword v10, v111, s[40:41]
	v_add_u32_e32 v10, 0x2000, v10
	v_fmac_f32_e32 v112, v111, v214
	global_store_dword v10, v112, s[40:41]
	v_add_u32_e32 v10, 0x2000, v10
	v_fmac_f32_e32 v113, v112, v215
	global_store_dword v10, v113, s[40:41]
	v_add_u32_e32 v10, 0x2000, v10
	v_fmac_f32_e32 v114, v113, v216
	global_store_dword v10, v114, s[40:41]
	v_add_u32_e32 v10, 0x2000, v10
	v_fmac_f32_e32 v115, v114, v217
	global_store_dword v10, v115, s[40:41]
	v_add_u32_e32 v10, 0x2000, v10
	v_fmac_f32_e32 v116, v115, v218
	global_store_dword v10, v116, s[40:41]
	v_add_u32_e32 v10, 0x2000, v10
	v_fmac_f32_e32 v117, v116, v219
	global_store_dword v10, v117, s[40:41]
	v_add_u32_e32 v10, 0x2000, v10
	v_fmac_f32_e32 v118, v117, v220
	global_store_dword v10, v118, s[40:41]
	v_add_u32_e32 v10, 0x2000, v10
	v_fmac_f32_e32 v119, v118, v221
	global_store_dword v10, v119, s[40:41]
	v_add_u32_e32 v10, 0x2000, v10
	v_fmac_f32_e32 v120, v119, v222
	global_store_dword v10, v120, s[40:41]
	v_add_u32_e32 v10, 0x2000, v10
	v_fmac_f32_e32 v121, v120, v223
	global_store_dword v10, v121, s[40:41]
	v_add_u32_e32 v10, 0x2000, v10
	v_fmac_f32_e32 v122, v121, v224
	global_store_dword v10, v122, s[40:41]
	v_add_u32_e32 v10, 0x2000, v10
	v_fmac_f32_e32 v123, v122, v225
	global_store_dword v10, v123, s[40:41]
	v_add_u32_e32 v10, 0x2000, v10
	v_fmac_f32_e32 v142, v123, v226
	global_store_dword v10, v142, s[40:41]
	v_add_u32_e32 v10, 0x2000, v10
	v_fmac_f32_e32 v143, v142, v227
	global_store_dword v10, v143, s[40:41]
	v_add_u32_e32 v10, 0x2000, v10
	v_fmac_f32_e32 v144, v143, v228
	global_store_dword v10, v144, s[40:41]
	v_add_u32_e32 v10, 0x2000, v10
	v_fmac_f32_e32 v145, v144, v229
	global_store_dword v10, v145, s[40:41]
	v_add_u32_e32 v10, 0x2000, v10
	v_fmac_f32_e32 v146, v145, v230
	global_store_dword v10, v146, s[40:41]
	v_add_u32_e32 v10, 0x2000, v10
	v_fmac_f32_e32 v147, v146, v231
	global_store_dword v10, v147, s[40:41]
	v_add_u32_e32 v10, 0x2000, v10
	v_fmac_f32_e32 v148, v147, v232
	global_store_dword v10, v148, s[40:41]
	v_add_u32_e32 v10, 0x2000, v10
	v_fmac_f32_e32 v149, v148, v233
	global_store_dword v10, v149, s[40:41]
	v_add_u32_e32 v10, 0x2000, v10
	v_fmac_f32_e32 v150, v149, v234
	global_store_dword v10, v150, s[40:41]
	v_add_u32_e32 v10, 0x2000, v10
	v_fmac_f32_e32 v151, v150, v235
	global_store_dword v10, v151, s[40:41]
	v_add_u32_e32 v10, 0x2000, v10
	v_fmac_f32_e32 v152, v151, v236
	global_store_dword v10, v152, s[40:41]
	v_add_u32_e32 v10, 0x2000, v10
	v_fmac_f32_e32 v153, v152, v237
	global_store_dword v10, v153, s[40:41]
	v_add_u32_e32 v10, 0x2000, v10
	v_fmac_f32_e32 v154, v153, v238
	global_store_dword v10, v154, s[40:41]
	v_add_u32_e32 v10, 0x2000, v10
	v_fmac_f32_e32 v155, v154, v239
	global_store_dword v10, v155, s[40:41]
	v_add_u32_e32 v10, 0x2000, v10
	v_fmac_f32_e32 v156, v155, v240
	global_store_dword v10, v156, s[40:41]
	v_add_u32_e32 v10, 0x2000, v10
	v_fmac_f32_e32 v157, v156, v241
	global_store_dword v10, v157, s[40:41]
	v_add_u32_e32 v10, 0x2000, v10
	v_fmac_f32_e32 v158, v157, v242
	global_store_dword v10, v158, s[40:41]
	v_add_u32_e32 v10, 0x2000, v10
	v_fmac_f32_e32 v159, v158, v243
	v_add_u32_e32 v1, s22, v1
	v_cmp_lt_i32_e32 vcc, s23, v1
	s_or_b64 s[18:19], vcc, s[18:19]
	v_add_u16_e32 v5, s22, v5
	s_andn2_b64 exec, exec, s[18:19]
	s_cbranch_execnz .LBB0_374

; __device__ __forceinline__ u32x4 pack8(const float* f) { u32x4 w; w.x = pk2(f[0], f[1]); w.y = pk2(f[2], f[3]); w.z = pk2(f[4], f[5]); w.w = pk2(f[6], f[7]); return w; }
; __device__ void tconv(unsigned char* smem, const float* src, int ldsrc, int col0, int N, int K, u16* dst, int ldd) {
;     float* T = (float*)smem;
;     const int tid = threadIdx.x, tilesN = N >> 6, ntile = tilesN * (K >> 6);
;     const int lr = tid >> 4, lc = (tid & 15) * 4;
;     const int sn = tid >> 3, sk = (tid & 7) * 8;
;     int tile = blockIdx.x;
;     f32x4 v0 = {0.f, 0.f, 0.f, 0.f}, v1 = {0.f, 0.f, 0.f, 0.f};
;     if (tile < ntile) { const int tn = tile % tilesN, tk = tile / tilesN; const float* s = src + (size_t)(tk * 64 + lr) * ldsrc + col0 + tn * 64 + lc;
;         v0 = __builtin_nontemporal_load((const f32x4*)s); v1 = __builtin_nontemporal_load((const f32x4*)(s + (size_t)32 * ldsrc)); }
;     for (; tile < ntile; tile += gridDim.x) {
;         const int tn = tile % tilesN, tk = tile / tilesN;
; #pragma unroll
;         for (int j = 0; j < 4; ++j) { T[lr * 65 + lc + j] = v0[j]; T[(lr + 32) * 65 + lc + j] = v1[j]; }
;         asm volatile("s_waitcnt lgkmcnt(0)" ::: "memory"); __builtin_amdgcn_s_barrier(); asm volatile("" ::: "memory");
;         const int nx = tile + gridDim.x;
;         if (nx < ntile) { const int tn2 = nx % tilesN, tk2 = nx / tilesN; const float* s = src + (size_t)(tk2 * 64 + lr) * ldsrc + col0 + tn2 * 64 + lc;
;             v0 = __builtin_nontemporal_load((const f32x4*)s); v1 = __builtin_nontemporal_load((const f32x4*)(s + (size_t)32 * ldsrc)); }
;         float f[8];
; #pragma unroll
;         for (int j = 0; j < 8; ++j) f[j] = T[(sk + j) * 65 + sn];
;         *(u32x4*)(dst + (size_t)(tn * 64 + sn) * ldd + tk * 64 + sk) = pack8(f);
;         asm volatile("s_waitcnt lgkmcnt(0)" ::: "memory"); __builtin_amdgcn_s_barrier(); asm volatile("" ::: "memory");
;     }
;     __syncthreads();
; }
.LBB0_1013:
	s_cmpk_lt_i32 s70, 0x800
	v_lshrrev_b32_e32 v1, 4, v103
	s_cselect_b64 s[0:1], -1, 0
	s_cmpk_gt_i32 s70, 0x7ff
	v_lshrrev_b32_e32 v14, 3, v103
	s_cbranch_scc1 .LBB0_1020
	s_waitcnt vmcnt(0) lgkmcnt(0)
	s_barrier
	v_readlane_b32 s40, v251, 28
	v_readlane_b32 s41, v251, 29
	v_and_b32_e32 v142, 0x3ff, v0
	v_lshrrev_b32_e32 v153, 4, v142
	v_and_b32_e32 v154, 15, v142
	v_lshlrev_b32_e32 v154, 4, v154
	v_lshlrev_b32_e32 v143, 16, v153
	v_add_u32_e32 v143, v143, v154
	v_mul_u32_u24_e32 v145, 0x104, v153
	v_add_u32_e32 v145, v145, v154
	v_add_u32_e32 v146, 0x2080, v145
	v_add_u32_e32 v147, 0x4100, v145
	v_add_u32_e32 v148, 0x6180, v145
	v_lshrrev_b32_e32 v153, 3, v142
	v_and_b32_e32 v154, 7, v142
	v_mul_u32_u24_e32 v149, 0x820, v154
	v_lshl_add_u32 v149, v153, 2, v149
	v_add_u32_e32 v150, 0x400, v149
	v_add_u32_e32 v151, 0x4100, v149
	v_add_u32_e32 v152, 0x4500, v149
	v_lshlrev_b32_e32 v144, 12, v153
	v_lshl_add_u32 v144, v154, 4, v144
	s_add_u32 s44, s64, 0x1c000000
	s_addc_u32 s45, s65, 0
	s_lshl_b32 s54, s62, 1
	s_mov_b32 s46, s70
	s_waitcnt lgkmcnt(0)
	s_add_u32 s40, s40, 0xc000
	s_addc_u32 s41, s41, 0
	s_add_u32 s42, s40, 0x200000
	s_addc_u32 s43, s41, 0
	s_add_i32 s47, s46, s62
	s_cmpk_lt_i32 s47, 0x800
	s_cselect_b32 s47, s47, s46
	s_and_b32 s52, s46, 0x3f
	s_lshr_b32 s53, s46, 6
	s_lshl_b32 s52, s52, 8
	s_lshl_b32 s53, s53, 22
	s_add_i32 s48, s52, s53
	s_and_b32 s52, s47, 0x3f
	s_lshr_b32 s53, s47, 6
	s_lshl_b32 s52, s52, 8
	s_lshl_b32 s53, s53, 22
	s_add_i32 s49, s52, s53
	v_add_u32_e32 v153, s48, v143
	v_add_u32_e32 v172, s49, v143
	global_load_dwordx4 v[70:73], v153, s[40:41] nt
	global_load_dwordx4 v[74:77], v153, s[42:43] nt
	global_load_dwordx4 v[78:81], v172, s[40:41] nt
	global_load_dwordx4 v[82:85], v172, s[42:43] nt
	s_waitcnt vmcnt(0)
TCV5_body:
	ds_write2_b32 v145, v70, v71 offset1:1
	ds_write2_b32 v145, v72, v73 offset0:2 offset1:3
	ds_write2_b32 v146, v74, v75 offset1:1
	ds_write2_b32 v146, v76, v77 offset0:2 offset1:3
	ds_write2_b32 v147, v78, v79 offset1:1
	ds_write2_b32 v147, v80, v81 offset0:2 offset1:3
	ds_write2_b32 v148, v82, v83 offset1:1
	ds_write2_b32 v148, v84, v85 offset0:2 offset1:3
	s_and_b32 s52, s46, 0x3f
	s_lshr_b32 s53, s46, 6
	s_lshl_b32 s52, s52, 18
	s_lshl_b32 s53, s53, 7
	s_add_i32 s50, s52, s53
	s_and_b32 s52, s47, 0x3f
	s_lshr_b32 s53, s47, 6
	s_lshl_b32 s52, s52, 18
	s_lshl_b32 s53, s53, 7
	s_add_i32 s51, s52, s53
	s_waitcnt lgkmcnt(0)
	s_barrier
	s_add_i32 s46, s46, s54
	s_cmpk_lt_i32 s46, 0x800
	s_cbranch_scc0 TCV5_noload
	s_add_i32 s47, s46, s62
	s_cmpk_lt_i32 s47, 0x800
	s_cselect_b32 s47, s47, s46
	s_and_b32 s52, s46, 0x3f
	s_lshr_b32 s53, s46, 6
	s_lshl_b32 s52, s52, 8
	s_lshl_b32 s53, s53, 22
	s_add_i32 s48, s52, s53
	s_and_b32 s52, s47, 0x3f
	s_lshr_b32 s53, s47, 6
	s_lshl_b32 s52, s52, 8
	s_lshl_b32 s53, s53, 22
	s_add_i32 s49, s52, s53
	v_add_u32_e32 v153, s48, v143
	v_add_u32_e32 v172, s49, v143
	global_load_dwordx4 v[70:73], v153, s[40:41] nt
	global_load_dwordx4 v[74:77], v153, s[42:43] nt
	global_load_dwordx4 v[78:81], v172, s[40:41] nt
	global_load_dwordx4 v[82:85], v172, s[42:43] nt
TCV5_noload:
	ds_read2_b32 v[156:157], v149 offset1:65
	ds_read2_b32 v[158:159], v149 offset0:130 offset1:195
	ds_read2_b32 v[160:161], v150 offset0:4 offset1:69
	ds_read2_b32 v[162:163], v150 offset0:134 offset1:199
	ds_read2_b32 v[164:165], v151 offset1:65
	ds_read2_b32 v[166:167], v151 offset0:130 offset1:195
	ds_read2_b32 v[168:169], v152 offset0:4 offset1:69
	ds_read2_b32 v[170:171], v152 offset0:134 offset1:199
	v_add_u32_e32 v154, s50, v144
	v_add_u32_e32 v155, s51, v144
	s_waitcnt lgkmcnt(7)
	v_cvt_pk_bf16_f32 v156, v156, v157
	s_waitcnt lgkmcnt(6)
	v_cvt_pk_bf16_f32 v157, v158, v159
	s_waitcnt lgkmcnt(5)
	v_cvt_pk_bf16_f32 v158, v160, v161
	s_waitcnt lgkmcnt(4)
	v_cvt_pk_bf16_f32 v159, v162, v163
	global_store_dwordx4 v154, v[156:159], s[44:45]
	s_waitcnt lgkmcnt(3)
	v_cvt_pk_bf16_f32 v164, v164, v165
	s_waitcnt lgkmcnt(2)
	v_cvt_pk_bf16_f32 v165, v166, v167
	s_waitcnt lgkmcnt(1)
	v_cvt_pk_bf16_f32 v166, v168, v169
	s_waitcnt lgkmcnt(0)
	v_cvt_pk_bf16_f32 v167, v170, v171
	global_store_dwordx4 v155, v[164:167], s[44:45]
	s_barrier
	s_cmpk_lt_i32 s46, 0x800
	s_waitcnt vmcnt(2)
	s_cbranch_scc1 TCV5_body
; __device__ __forceinline__ u32x4 pack8(const float* f) { u32x4 w; w.x = pk2(f[0], f[1]); w.y = pk2(f[2], f[3]); w.z = pk2(f[4], f[5]); w.w = pk2(f[6], f[7]); return w; }
; __device__ void tconv(unsigned char* smem, const float* src, int ldsrc, int col0, int N, int K, u16* dst, int ldd) {
;     float* T = (float*)smem;
;     const int tid = threadIdx.x, tilesN = N >> 6, ntile = tilesN * (K >> 6);
;     const int lr = tid >> 4, lc = (tid & 15) * 4;
;     const int sn = tid >> 3, sk = (tid & 7) * 8;
;     int tile = blockIdx.x;
;     f32x4 v0 = {0.f, 0.f, 0.f, 0.f}, v1 = {0.f, 0.f, 0.f, 0.f};
;     if (tile < ntile) { const int tn = tile % tilesN, tk = tile / tilesN; const float* s = src + (size_t)(tk * 64 + lr) * ldsrc + col0 + tn * 64 + lc;
;         v0 = __builtin_nontemporal_load((const f32x4*)s); v1 = __builtin_nontemporal_load((const f32x4*)(s + (size_t)32 * ldsrc)); }
;     for (; tile < ntile; tile += gridDim.x) {
;         const int tn = tile % tilesN, tk = tile / tilesN;
; #pragma unroll
;         for (int j = 0; j < 4; ++j) { T[lr * 65 + lc + j] = v0[j]; T[(lr + 32) * 65 + lc + j] = v1[j]; }
;         asm volatile("s_waitcnt lgkmcnt(0)" ::: "memory"); __builtin_amdgcn_s_barrier(); asm volatile("" ::: "memory");
;         const int nx = tile + gridDim.x;
;         if (nx < ntile) { const int tn2 = nx % tilesN, tk2 = nx / tilesN; const float* s = src + (size_t)(tk2 * 64 + lr) * ldsrc + col0 + tn2 * 64 + lc;
;             v0 = __builtin_nontemporal_load((const f32x4*)s); v1 = __builtin_nontemporal_load((const f32x4*)(s + (size_t)32 * ldsrc)); }
;         float f[8];
; #pragma unroll
;         for (int j = 0; j < 8; ++j) f[j] = T[(sk + j) * 65 + sn];
;         *(u32x4*)(dst + (size_t)(tn * 64 + sn) * ldd + tk * 64 + sk) = pack8(f);
;         asm volatile("s_waitcnt lgkmcnt(0)" ::: "memory"); __builtin_amdgcn_s_barrier(); asm volatile("" ::: "memory");
;     }
;     __syncthreads();
; }
.LBB0_1020:
	s_andn2_b64 vcc, exec, s[0:1]
	s_barrier
	s_cbranch_vccnz .LBB0_1027
	s_waitcnt vmcnt(0) lgkmcnt(0)
	s_barrier
	v_readlane_b32 s40, v250, 15
	v_readlane_b32 s41, v250, 16
	v_and_b32_e32 v142, 0x3ff, v0
	v_lshrrev_b32_e32 v153, 4, v142
	v_and_b32_e32 v154, 15, v142
	v_lshlrev_b32_e32 v154, 4, v154
	v_lshlrev_b32_e32 v143, 13, v153
	v_add_u32_e32 v143, v143, v154
	v_mul_u32_u24_e32 v145, 0x104, v153
	v_add_u32_e32 v145, v145, v154
	v_add_u32_e32 v146, 0x2080, v145
	v_add_u32_e32 v147, 0x4100, v145
	v_add_u32_e32 v148, 0x6180, v145
	v_lshrrev_b32_e32 v153, 3, v142
	v_and_b32_e32 v154, 7, v142
	v_mul_u32_u24_e32 v149, 0x820, v154
	v_lshl_add_u32 v149, v153, 2, v149
	v_add_u32_e32 v150, 0x400, v149
	v_add_u32_e32 v151, 0x4100, v149
	v_add_u32_e32 v152, 0x4500, v149
	v_lshlrev_b32_e32 v144, 13, v153
	v_lshl_add_u32 v144, v154, 4, v144
	s_add_u32 s44, s64, 0x1d000000
	s_addc_u32 s45, s65, 0
	s_lshl_b32 s54, s62, 1
	s_mov_b32 s46, s70
	s_waitcnt lgkmcnt(0)
	s_add_u32 s42, s40, 0x40000
	s_addc_u32 s43, s41, 0
	s_add_i32 s47, s46, s62
	s_cmpk_lt_i32 s47, 0x800
	s_cselect_b32 s47, s47, s46
	s_and_b32 s52, s46, 0x1f
	s_lshr_b32 s53, s46, 5
	s_lshl_b32 s52, s52, 8
	s_lshl_b32 s53, s53, 19
	s_add_i32 s48, s52, s53
	s_and_b32 s52, s47, 0x1f
	s_lshr_b32 s53, s47, 5
	s_lshl_b32 s52, s52, 8
	s_lshl_b32 s53, s53, 19
	s_add_i32 s49, s52, s53
	v_add_u32_e32 v153, s48, v143
	v_add_u32_e32 v172, s49, v143
	global_load_dwordx4 v[70:73], v153, s[40:41] nt
	global_load_dwordx4 v[74:77], v153, s[42:43] nt
	global_load_dwordx4 v[78:81], v172, s[40:41] nt
	global_load_dwordx4 v[82:85], v172, s[42:43] nt
	s_waitcnt vmcnt(0)
TCV6_body:
	ds_write2_b32 v145, v70, v71 offset1:1
	ds_write2_b32 v145, v72, v73 offset0:2 offset1:3
	ds_write2_b32 v146, v74, v75 offset1:1
	ds_write2_b32 v146, v76, v77 offset0:2 offset1:3
	ds_write2_b32 v147, v78, v79 offset1:1
	ds_write2_b32 v147, v80, v81 offset0:2 offset1:3
	ds_write2_b32 v148, v82, v83 offset1:1
	ds_write2_b32 v148, v84, v85 offset0:2 offset1:3
	s_and_b32 s52, s46, 0x1f
	s_lshr_b32 s53, s46, 5
	s_lshl_b32 s52, s52, 19
	s_lshl_b32 s53, s53, 7
	s_add_i32 s50, s52, s53
	s_and_b32 s52, s47, 0x1f
	s_lshr_b32 s53, s47, 5
	s_lshl_b32 s52, s52, 19
	s_lshl_b32 s53, s53, 7
	s_add_i32 s51, s52, s53
	s_waitcnt lgkmcnt(0)
	s_barrier
	s_add_i32 s46, s46, s54
	s_cmpk_lt_i32 s46, 0x800
	s_cbranch_scc0 TCV6_noload
	s_add_i32 s47, s46, s62
	s_cmpk_lt_i32 s47, 0x800
	s_cselect_b32 s47, s47, s46
	s_and_b32 s52, s46, 0x1f
	s_lshr_b32 s53, s46, 5
	s_lshl_b32 s52, s52, 8
	s_lshl_b32 s53, s53, 19
	s_add_i32 s48, s52, s53
	s_and_b32 s52, s47, 0x1f
	s_lshr_b32 s53, s47, 5
	s_lshl_b32 s52, s52, 8
	s_lshl_b32 s53, s53, 19
	s_add_i32 s49, s52, s53
	v_add_u32_e32 v153, s48, v143
	v_add_u32_e32 v172, s49, v143
	global_load_dwordx4 v[70:73], v153, s[40:41] nt
	global_load_dwordx4 v[74:77], v153, s[42:43] nt
	global_load_dwordx4 v[78:81], v172, s[40:41] nt
	global_load_dwordx4 v[82:85], v172, s[42:43] nt
TCV6_noload:
	ds_read2_b32 v[156:157], v149 offset1:65
	ds_read2_b32 v[158:159], v149 offset0:130 offset1:195
	ds_read2_b32 v[160:161], v150 offset0:4 offset1:69
	ds_read2_b32 v[162:163], v150 offset0:134 offset1:199
	ds_read2_b32 v[164:165], v151 offset1:65
	ds_read2_b32 v[166:167], v151 offset0:130 offset1:195
	ds_read2_b32 v[168:169], v152 offset0:4 offset1:69
	ds_read2_b32 v[170:171], v152 offset0:134 offset1:199
	v_add_u32_e32 v154, s50, v144
	v_add_u32_e32 v155, s51, v144
	s_waitcnt lgkmcnt(7)
	v_cvt_pk_bf16_f32 v156, v156, v157
	s_waitcnt lgkmcnt(6)
	v_cvt_pk_bf16_f32 v157, v158, v159
	s_waitcnt lgkmcnt(5)
	v_cvt_pk_bf16_f32 v158, v160, v161
	s_waitcnt lgkmcnt(4)
	v_cvt_pk_bf16_f32 v159, v162, v163
	global_store_dwordx4 v154, v[156:159], s[44:45]
	s_waitcnt lgkmcnt(3)
	v_cvt_pk_bf16_f32 v164, v164, v165
	s_waitcnt lgkmcnt(2)
	v_cvt_pk_bf16_f32 v165, v166, v167
	s_waitcnt lgkmcnt(1)
	v_cvt_pk_bf16_f32 v166, v168, v169
	s_waitcnt lgkmcnt(0)
	v_cvt_pk_bf16_f32 v167, v170, v171
	global_store_dwordx4 v155, v[164:167], s[44:45]
	s_barrier
	s_cmpk_lt_i32 s46, 0x800
	s_waitcnt vmcnt(2)
	s_cbranch_scc1 TCV6_body
